# SSD scan pass off-diagonal term: all four state-fragment LDS reads issued right after the barrier with counted lgkmcnt (two were issued late, each exposing an LDS round trip); on top of v41
# baseline (speedup 1.0000x reference)
; __device__ __forceinline__ f32x4 mfma16(bf16x8 a, bf16x8 b, f32x4 c) { return __builtin_amdgcn_mfma_f32_16x16x32_bf16(a, b, c, 0, 0, 0); }
; __device__ __forceinline__ void ssd_scan_item(CParams& p, int j2, int b, int dir, int h, int pq, bf16_t* smem) {
;     ...
;         lds_sync();
;         load_small(S, row2);
;         f32x4 yo[2];
;         yo[0] = (f32x4){0.f, 0.f, 0.f, 0.f}; yo[1] = (f32x4){0.f, 0.f, 0.f, 0.f};
; #pragma unroll
;         for (int ks = 0; ks < 4; ++ks) {
;             const bf16x8 hf = lds16(sH + l16 * SST + ks * 32 + quad * 8);
; #pragma unroll
;             for (int i = 0; i < 2; ++i) yo[i] = mfma16(hf, __builtin_bit_cast(bf16x8, S.cf[i][ks]), yo[i]);
;         }
;         __builtin_amdgcn_sched_barrier(0);
;         load_cf(S, row2);
; #pragma unroll
;         for (int i = 0; i < 2; ++i) {
;             const float e = seacs[wave * 32 + i * 16 + l16];
;             const float o0 = __uint_as_float(S.yold[i].x << 16), o1 = __uint_as_float(S.yold[i].x & 0xffff0000u);
;             const float o2 = __uint_as_float(S.yold[i].y << 16), o3 = __uint_as_float(S.yold[i].y & 0xffff0000u);
;             st4bf(Y + (size_t)((row0 >> 4) + i) * (64 * 512), yo[i][0] * e + o0, yo[i][1] * e + o1, yo[i][2] * e + o2, yo[i][3] * e + o3);
;         }
;         __builtin_amdgcn_sched_barrier(0);
;         load_yold(S, row2);
.LBB0_478:
	s_or_b64 exec, exec, s[20:21]
	s_waitcnt lgkmcnt(0)
	s_barrier
	ds_read_b128 v[88:91], v170 offset:4352
	ds_read_b128 v[178:181], v170 offset:4416
	ds_read_b128 v[220:223], v170 offset:4480
	ds_read_b128 v[224:227], v170 offset:4544
	s_min_u32 s22, s77, 63
	s_add_i32 s78, s77, -2
	s_and_b64 s[20:21], s[72:73], exec
	s_cselect_b32 s20, s78, s19
	s_lshl_b32 s20, s20, 7
	s_add_i32 s23, s20, s17
	s_cmp_eq_u32 s77, 0
	s_cselect_b64 s[20:21], -1, 0
	s_waitcnt lgkmcnt(3)
	v_mfma_f32_16x16x32_bf16 v[16:19], v[88:91], v[16:19], 0
	s_and_b64 s[24:25], s[20:21], exec
	s_cselect_b32 s38, s16, s23
	s_lshl_b32 s24, s22, 7
	s_waitcnt vmcnt(30)
	v_mfma_f32_16x16x32_bf16 v[28:31], v[88:91], v[28:31], 0
	s_nop 0
	s_xor_b32 s25, s24, 0x1f80
	s_and_b64 s[22:23], s[72:73], exec
	s_cselect_b32 s22, s24, s25
	s_waitcnt lgkmcnt(2)
	v_mfma_f32_16x16x32_bf16 v[8:11], v[178:181], v[8:11], v[16:19]
	s_or_b32 s22, s22, s17
	s_ashr_i32 s23, s22, 31
	v_lshl_add_u64 v[182:183], s[22:23], 1, v[144:145]
	s_waitcnt vmcnt(29)
	v_mfma_f32_16x16x32_bf16 v[16:19], v[178:181], v[24:27], v[28:31]
	s_nop 0
	s_nop 1
	v_or_b32_e32 v28, s22, v160
	v_ashrrev_i32_e32 v29, 31, v28
	s_waitcnt lgkmcnt(1)
	v_mfma_f32_16x16x32_bf16 v[4:7], v[220:223], v[4:7], v[8:11]
	s_nop 2
	v_lshlrev_b64 v[8:9], 8, v[28:29]
	v_or_b32_e32 v28, 64, v28
	v_ashrrev_i32_e32 v29, 31, v28
	v_lshl_add_u64 v[30:31], s[92:93], 0, v[8:9]
	s_waitcnt vmcnt(28)
	v_mfma_f32_16x16x32_bf16 v[8:11], v[220:223], v[20:23], v[16:19]
	s_nop 2
	v_lshlrev_b64 v[16:17], 8, v[28:29]
	v_lshl_add_u64 v[16:17], s[92:93], 0, v[16:17]
	global_load_dwordx4 v[88:91], v[182:183], off
	global_load_dword v161, v[30:31], off
	global_load_dword v162, v[16:17], off
	s_waitcnt lgkmcnt(0)
	v_mfma_f32_16x16x32_bf16 v[178:181], v[224:227], v[0:3], v[4:7]
	s_waitcnt vmcnt(30)
	v_mfma_f32_16x16x32_bf16 v[182:185], v[224:227], v[12:15], v[8:11]
	s_ashr_i32 s26, s22, 4
	s_ashr_i32 s27, s26, 31
	s_lshl_b64 s[24:25], s[26:27], 14
	v_lshl_add_u64 v[0:1], v[146:147], 0, s[24:25]
	s_or_b32 s24, s26, 1
	s_ashr_i32 s25, s24, 31
	s_lshl_b64 vcc, s[24:25], 14
	v_lshl_add_u64 v[12:13], v[146:147], 0, vcc
	global_load_dwordx4 v[16:19], v[0:1], off
	global_load_dwordx4 v[8:11], v[0:1], off offset:1024
	global_load_dwordx4 v[4:7], v[0:1], off offset:2048
	s_nop 0
	global_load_dwordx4 v[0:3], v[0:1], off offset:3072
	s_nop 0
	global_load_dwordx4 v[28:31], v[12:13], off
	global_load_dwordx4 v[24:27], v[12:13], off offset:1024
	global_load_dwordx4 v[20:23], v[12:13], off offset:2048
	s_nop 0
	global_load_dwordx4 v[12:15], v[12:13], off offset:3072
	v_add_u32_e32 v177, 0x2000, v171
	ds_read2_b32 v[186:187], v177 offset0:128 offset1:144
	s_ashr_i32 vcc_lo, s38, 4
	s_ashr_i32 vcc_hi, vcc_lo, 31
	v_lshlrev_b32_e32 v190, 16, v156
	v_and_b32_e32 v191, 0xffff0000, v156
	v_lshlrev_b32_e32 v156, 16, v157
	v_and_b32_e32 v157, 0xffff0000, v157
	s_lshl_b64 s[38:39], vcc, 16
	s_waitcnt lgkmcnt(0)
	v_pk_fma_f32 v[178:179], v[178:179], v[186:187], v[190:191] op_sel_hi:[1,0,1]
	v_pk_fma_f32 v[156:157], v[180:181], v[186:187], v[156:157] op_sel_hi:[1,0,1]
	v_lshl_add_u64 v[188:189], v[148:149], 0, s[38:39]
	v_cvt_pk_bf16_f32 v178, v178, v179
	v_cvt_pk_bf16_f32 v179, v156, v157
	s_or_b32 s38, vcc_lo, 1
	global_store_dwordx2 v[188:189], v[178:179], off
	s_ashr_i32 s39, s38, 31
	v_lshlrev_b32_e32 v178, 16, v152
	v_and_b32_e32 v179, 0xffff0000, v152
	v_mov_b32_e32 v152, v187
	v_lshlrev_b32_e32 v180, 16, v153
	v_and_b32_e32 v181, 0xffff0000, v153
	s_lshl_b64 s[38:39], s[38:39], 16
	v_pk_fma_f32 v[178:179], v[182:183], v[152:153], v[178:179] op_sel_hi:[1,0,1]
	v_pk_fma_f32 v[152:153], v[184:185], v[152:153], v[180:181] op_sel_hi:[1,0,1]
	v_lshl_add_u64 v[156:157], v[148:149], 0, s[38:39]
	v_cvt_pk_bf16_f32 v178, v178, v179
	v_cvt_pk_bf16_f32 v179, v152, v153
	global_store_dwordx2 v[156:157], v[178:179], off
	v_mov_b32_e32 v152, 0
	s_and_b64 vcc, exec, s[42:43]
	v_mov_b32_e32 v156, 0
	v_mov_b32_e32 v157, 0
	s_cbranch_vccnz .LBB0_480
	s_lshl_b64 s[26:27], s[26:27], 16
	v_lshl_add_u64 v[156:157], v[148:149], 0, s[26:27]
	global_load_dwordx2 v[156:157], v[156:157], off

; __device__ __forceinline__ f32x4 mfma16(bf16x8 a, bf16x8 b, f32x4 c) { return __builtin_amdgcn_mfma_f32_16x16x32_bf16(a, b, c, 0, 0, 0); }
; __device__ __forceinline__ void ssd_scan_item(CParams& p, int j2, int b, int dir, int h, int pq, bf16_t* smem) {
;     ...
;         lds_sync();
;         load_small(S, row2);
;         f32x4 yo[2];
;         yo[0] = (f32x4){0.f, 0.f, 0.f, 0.f}; yo[1] = (f32x4){0.f, 0.f, 0.f, 0.f};
; #pragma unroll
;         for (int ks = 0; ks < 4; ++ks) {
;             const bf16x8 hf = lds16(sH + l16 * SST + ks * 32 + quad * 8);
; #pragma unroll
;             for (int i = 0; i < 2; ++i) yo[i] = mfma16(hf, __builtin_bit_cast(bf16x8, S.cf[i][ks]), yo[i]);
;         }
;         __builtin_amdgcn_sched_barrier(0);
;         load_cf(S, row2);
; #pragma unroll
;         for (int i = 0; i < 2; ++i) {
;             const float e = seacs[wave * 32 + i * 16 + l16];
;             const float o0 = __uint_as_float(S.yold[i].x << 16), o1 = __uint_as_float(S.yold[i].x & 0xffff0000u);
;             const float o2 = __uint_as_float(S.yold[i].y << 16), o3 = __uint_as_float(S.yold[i].y & 0xffff0000u);
;             st4bf(Y + (size_t)((row0 >> 4) + i) * (64 * 512), yo[i][0] * e + o0, yo[i][1] * e + o1, yo[i][2] * e + o2, yo[i][3] * e + o3);
;         }
;         __builtin_amdgcn_sched_barrier(0);
;         load_yold(S, row2);
.LBB0_496:
	s_or_b64 exec, exec, s[22:23]
	s_waitcnt lgkmcnt(0)
	s_barrier
	ds_read_b128 v[108:111], v170 offset:4352
	ds_read_b128 v[178:181], v170 offset:4416
	ds_read_b128 v[220:223], v170 offset:4480
	ds_read_b128 v[224:227], v170 offset:4544
	s_add_i32 s77, s77, 1
	s_min_u32 s22, s77, 63
	s_add_i32 s23, s19, -1
	s_add_i32 s26, s78, 1
	s_and_b64 s[24:25], s[72:73], exec
	s_cselect_b32 s23, s26, s23
	s_lshl_b32 s23, s23, 7
	s_add_i32 s23, s23, s17
	s_waitcnt vmcnt(36) lgkmcnt(3)
	v_mfma_f32_16x16x32_bf16 v[60:63], v[108:111], v[60:63], 0
	s_and_b64 s[20:21], s[20:21], exec
	s_cselect_b32 s27, s18, s23
	s_lshl_b32 s22, s22, 7
	s_waitcnt vmcnt(32)
	v_mfma_f32_16x16x32_bf16 v[68:71], v[108:111], v[68:71], 0
	s_nop 0
	s_xor_b32 s23, s22, 0x1f80
	s_and_b64 s[20:21], s[72:73], exec
	s_cselect_b32 s20, s22, s23
	s_waitcnt lgkmcnt(2)
	v_mfma_f32_16x16x32_bf16 v[48:51], v[178:181], v[48:51], v[60:63]
	s_or_b32 s20, s20, s17
	s_ashr_i32 s21, s20, 31
	v_lshl_add_u64 v[182:183], s[20:21], 1, v[144:145]
	s_waitcnt vmcnt(31)
	v_mfma_f32_16x16x32_bf16 v[60:63], v[178:181], v[64:67], v[68:71]
	s_nop 0
	s_nop 1
	v_or_b32_e32 v68, s20, v160
	v_ashrrev_i32_e32 v69, 31, v68
	s_waitcnt lgkmcnt(1)
	v_mfma_f32_16x16x32_bf16 v[44:47], v[220:223], v[44:47], v[48:51]
	s_nop 2
	v_lshlrev_b64 v[48:49], 8, v[68:69]
	v_or_b32_e32 v68, 64, v68
	v_ashrrev_i32_e32 v69, 31, v68
	v_lshl_add_u64 v[70:71], s[92:93], 0, v[48:49]
	s_waitcnt vmcnt(30)
	v_mfma_f32_16x16x32_bf16 v[48:51], v[220:223], v[56:59], v[60:63]
	v_lshlrev_b64 v[56:57], 8, v[68:69]
	v_lshl_add_u64 v[56:57], s[92:93], 0, v[56:57]
	global_load_dwordx4 v[108:111], v[182:183], off
	global_load_dword v173, v[70:71], off
	global_load_dword v175, v[56:57], off
	s_waitcnt lgkmcnt(0)
	v_mfma_f32_16x16x32_bf16 v[178:181], v[224:227], v[40:43], v[44:47]
	s_waitcnt vmcnt(32)
	v_mfma_f32_16x16x32_bf16 v[182:185], v[224:227], v[52:55], v[48:51]
	s_ashr_i32 s24, s20, 4
	s_ashr_i32 s25, s24, 31
	s_lshl_b64 s[22:23], s[24:25], 14
	v_lshl_add_u64 v[40:41], v[146:147], 0, s[22:23]
	s_or_b32 s22, s24, 1
	s_ashr_i32 s23, s22, 31
	s_lshl_b64 s[38:39], s[22:23], 14
	v_lshl_add_u64 v[52:53], v[146:147], 0, s[38:39]
	global_load_dwordx4 v[60:63], v[40:41], off
	global_load_dwordx4 v[48:51], v[40:41], off offset:1024
	global_load_dwordx4 v[44:47], v[40:41], off offset:2048
	s_nop 0
	global_load_dwordx4 v[40:43], v[40:41], off offset:3072
	s_nop 0
	global_load_dwordx4 v[68:71], v[52:53], off
	global_load_dwordx4 v[64:67], v[52:53], off offset:1024
	global_load_dwordx4 v[56:59], v[52:53], off offset:2048
	s_nop 0
	global_load_dwordx4 v[52:55], v[52:53], off offset:3072
	ds_read2_b32 v[176:177], v177 offset0:128 offset1:144
	s_ashr_i32 s38, s27, 4
	s_ashr_i32 s39, s38, 31
	v_lshlrev_b32_e32 v188, 16, v150
	v_and_b32_e32 v189, 0xffff0000, v150
	v_lshlrev_b32_e32 v150, 16, v151
	v_and_b32_e32 v151, 0xffff0000, v151
	s_lshl_b64 s[70:71], s[38:39], 16
	s_waitcnt lgkmcnt(0)
	v_pk_fma_f32 v[178:179], v[178:179], v[176:177], v[188:189] op_sel_hi:[1,0,1]
	v_pk_fma_f32 v[150:151], v[180:181], v[176:177], v[150:151] op_sel_hi:[1,0,1]
	v_lshl_add_u64 v[186:187], v[148:149], 0, s[70:71]
	v_cvt_pk_bf16_f32 v178, v178, v179
	v_cvt_pk_bf16_f32 v179, v150, v151
	global_store_dwordx2 v[186:187], v[178:179], off
	s_or_b32 s38, s38, 1
	v_lshlrev_b32_e32 v178, 16, v158
	v_and_b32_e32 v179, 0xffff0000, v158
	v_mov_b32_e32 v158, v177
	s_ashr_i32 s39, s38, 31
	v_pk_fma_f32 v[176:177], v[182:183], v[158:159], v[178:179] op_sel_hi:[1,0,1]
	v_lshlrev_b32_e32 v178, 16, v159
	v_and_b32_e32 v179, 0xffff0000, v159
	s_lshl_b64 s[38:39], s[38:39], 16
	v_pk_fma_f32 v[158:159], v[184:185], v[158:159], v[178:179] op_sel_hi:[1,0,1]
	v_lshl_add_u64 v[150:151], v[148:149], 0, s[38:39]
	v_cvt_pk_bf16_f32 v176, v176, v177
	v_cvt_pk_bf16_f32 v177, v158, v159
	global_store_dwordx2 v[150:151], v[176:177], off
	v_mov_b32_e32 v158, 0
	s_and_b64 vcc, exec, s[42:43]
	v_mov_b32_e32 v150, 0
	v_mov_b32_e32 v151, 0
	s_cbranch_vccnz .LBB0_498
	s_lshl_b64 s[24:25], s[24:25], 16
	v_lshl_add_u64 v[150:151], v[148:149], 0, s[24:25]
	global_load_dwordx2 v[150:151], v[150:151], off
